# P6 epilogue: second half's 16 x2/PLE operand quads also come through LDS (16 LDS-DMAs issued right after the first half's LDS reads, read back by ds_read_b128 where the global loads were)
# speedup vs baseline: 1.0045x; 1.0028x over previous
; __device__ __forceinline__ void row_rstd8(const float* SS, int row0, int fq, float (&rs)[2][4]) {
; #pragma unroll
;     for (int ai = 0; ai < 2; ++ai)
; #pragma unroll
;         for (int m = 0; m < 4; ++m) { const f32x4 t = *(const f32x4*)(SS + (size_t)(row0 + ai * HALF + m * 16) * 16 + 4 * fq); rs[ai][m] = (t[0] + t[1]) + (t[2] + t[3]); }
; #pragma unroll
;     for (int ai = 0; ai < 2; ++ai)
; #pragma unroll
;         for (int m = 0; m < 4; ++m) { float v = sum_fq(rs[ai][m]); rs[ai][m] = rsqrtf(v * (1.f / DM) + EPS); }
;     __device__ __forceinline__ void operator()(const f32x4 (&acc)[2][2][4][2], const Unit& u, int wr, int wc, int fr, int fq) const {
;         const int row0 = u.pm * BM + wr * 64 + fr, col0 = u.pn * BM + wc * 32 + 8 * fq;
;         float rs[2][4];
;         if (u.pm == rtab_pm) {
; #pragma unroll
;             for (int ai = 0; ai < 2; ++ai)
; #pragma unroll
;                 for (int m = 0; m < 4; ++m) rs[ai][m] = rtab[wr * 64 + fr + ai * HALF + m * 16];
;         } else row_rstd8(SS, row0, fq, rs);
.LBB0_1036:
	v_lshl_add_u32 v134, s2, 8, v198
	v_lshl_or_b32 v250, s58, 8, v201
	v_lshlrev_b32_e32 v250, 1, v250
	v_lshl_add_u32 v250, v134, 11, v250
	v_or_b32_e32 v132, 16, v134
	v_or_b32_e32 v130, 32, v134
	v_or_b32_e32 v128, 48, v134
	s_cmp_lg_u32 s2, s17
	v_ashrrev_i32_e32 v133, 31, v132
	s_mov_b64 s[2:3], -1
	v_ashrrev_i32_e32 v135, 31, v134
	v_ashrrev_i32_e32 v131, 31, v130
	v_ashrrev_i32_e32 v129, 31, v128
	v_add_u32_e32 v136, 0x80, v134
	s_cbranch_scc0 .LBB0_1038
	v_lshlrev_b64 v[138:139], 6, v[134:135]
	v_lshlrev_b64 v[142:143], 6, v[132:133]
	v_lshl_add_u64 v[154:155], v[168:169], 0, v[138:139]
	v_lshl_add_u64 v[142:143], v[168:169], 0, v[142:143]
	v_lshlrev_b64 v[146:147], 6, v[130:131]
	global_load_dwordx4 v[138:141], v[154:155], off
	v_lshl_add_u64 v[146:147], v[168:169], 0, v[146:147]
	global_load_dwordx4 v[142:145], v[142:143], off
	v_lshlrev_b64 v[150:151], 6, v[128:129]
	global_load_dwordx4 v[146:149], v[146:147], off
	v_lshl_add_u64 v[150:151], v[168:169], 0, v[150:151]
	global_load_dwordx4 v[150:153], v[150:151], off
	v_add_u32_e32 v182, 0x80, v134
	v_ashrrev_i32_e32 v183, 31, v182
	v_add_co_u32_e32 v158, vcc, s48, v154
	v_lshlrev_b64 v[184:185], 6, v[182:183]
	s_nop 0
	v_addc_co_u32_e32 v159, vcc, 0, v155, vcc
	v_lshl_add_u64 v[184:185], v[168:169], 0, v[184:185]
	global_load_dwordx4 v[154:157], v[158:159], off offset:2048
	global_load_dwordx4 v[178:181], v[158:159], off offset:3072
	s_nop 0
	global_load_dwordx4 v[184:187], v[184:185], off
	s_nop 0
	global_load_dwordx4 v[188:191], v[158:159], off offset:1024
	v_mov_b64_e32 v[158:159], s[18:19]
	s_waitcnt vmcnt(0)
	v_mov_b32_e32 v192, v139
	v_mov_b32_e32 v193, v140
	v_mov_b32_e32 v139, v141
	v_mov_b32_e32 v140, v143
	v_mov_b32_e32 v141, v144
	v_mov_b32_e32 v143, v145
	v_mov_b32_e32 v144, v147
	v_mov_b32_e32 v145, v148
	v_mov_b32_e32 v147, v149
	v_pk_add_f32 v[138:139], v[192:193], v[138:139]
	v_pk_add_f32 v[140:141], v[140:141], v[142:143]
	v_pk_add_f32 v[142:143], v[144:145], v[146:147]
	v_pk_add_f32 v[138:139], v[138:139], v[138:139] op_sel:[0,1] op_sel_hi:[1,0]
	v_pk_add_f32 v[140:141], v[140:141], v[140:141] op_sel:[0,1] op_sel_hi:[1,0]
	v_pk_add_f32 v[142:143], v[142:143], v[142:143] op_sel:[0,1] op_sel_hi:[1,0]
	v_mov_b32_e32 v137, v138
	v_mov_b32_e32 v141, v140
	v_mov_b32_e32 v143, v142
	v_permlane32_swap_b32_e32 v138, v137
	v_permlane32_swap_b32_e32 v140, v141
	v_permlane32_swap_b32_e32 v142, v143
	v_add_f32_e32 v139, v138, v137
	v_add_f32_e32 v138, v140, v141
	v_add_f32_e32 v141, v142, v143
	v_mov_b32_e32 v143, v139
	v_mov_b32_e32 v142, v138
	s_nop 0
	v_permlane16_swap_b32_e32 v139, v143
	v_permlane16_swap_b32_e32 v138, v142
	v_pk_add_f32 v[138:139], v[138:139], v[142:143]
	v_mov_b32_e32 v148, v151
	v_mov_b32_e32 v149, v152
	v_mov_b32_e32 v151, v153
	v_pk_fma_f32 v[138:139], v[138:139], s[16:17], v[158:159] op_sel_hi:[1,0,0]
	v_pk_add_f32 v[144:145], v[148:149], v[150:151]
	v_mul_f32_e32 v137, 0x4b800000, v139
	v_cmp_gt_f32_e32 vcc, s57, v139
	v_pk_add_f32 v[144:145], v[144:145], v[144:145] op_sel:[0,1] op_sel_hi:[1,0]
	v_mul_f32_e32 v140, 0x4b800000, v138
	v_cndmask_b32_e32 v137, v139, v137, vcc
	v_rsq_f32_e32 v139, v137
	v_mov_b32_e32 v137, v144
	v_cmp_gt_f32_e64 s[2:3], s57, v138
	s_nop 0
	v_permlane32_swap_b32_e32 v144, v137
	v_cndmask_b32_e64 v138, v138, v140, s[2:3]
	v_add_f32_e32 v140, v144, v137
	v_mov_b32_e32 v145, v141
	v_mov_b32_e32 v144, v140
	s_nop 0
	v_permlane16_swap_b32_e32 v141, v145
	v_permlane16_swap_b32_e32 v140, v144
	v_pk_add_f32 v[140:141], v[140:141], v[144:145]
	v_rsq_f32_e32 v138, v138
	v_pk_fma_f32 v[140:141], v[140:141], s[16:17], v[158:159] op_sel_hi:[1,0,0]
	v_mov_b32_e32 v150, v185
	v_mul_f32_e32 v137, 0x4b800000, v141
	v_cmp_gt_f32_e64 s[4:5], s57, v141
	v_cmp_gt_f32_e64 s[6:7], s57, v140
	v_mov_b32_e32 v151, v186
	v_cndmask_b32_e64 v137, v141, v137, s[4:5]
	v_rsq_f32_e32 v141, v137
	v_mul_f32_e32 v137, 0x4b800000, v140
	v_cndmask_b32_e64 v137, v140, v137, s[6:7]
	v_mov_b32_e32 v185, v187
	v_rsq_f32_e32 v140, v137
	v_pk_add_f32 v[150:151], v[150:151], v[184:185]
	v_mov_b32_e32 v152, v189
	v_mov_b32_e32 v153, v190
	v_mov_b32_e32 v189, v191
	v_pk_add_f32 v[150:151], v[150:151], v[150:151] op_sel:[0,1] op_sel_hi:[1,0]
	v_pk_add_f32 v[152:153], v[152:153], v[188:189]
	v_pk_mul_f32 v[142:143], v[138:139], s[22:23] op_sel_hi:[1,0]
	v_mov_b32_e32 v137, v150
	v_pk_add_f32 v[152:153], v[152:153], v[152:153] op_sel:[0,1] op_sel_hi:[1,0]
	v_cndmask_b32_e64 v195, v138, v142, s[2:3]
	v_cndmask_b32_e32 v194, v139, v143, vcc
	v_pk_mul_f32 v[138:139], v[140:141], s[22:23] op_sel_hi:[1,0]
	v_permlane32_swap_b32_e32 v150, v137
	v_cndmask_b32_e64 v188, v141, v139, s[4:5]
	v_add_f32_e32 v139, v150, v137
	v_mov_b32_e32 v137, v152
	s_nop 1
	v_permlane32_swap_b32_e32 v152, v137
	v_cndmask_b32_e64 v189, v140, v138, s[6:7]
	v_add_f32_e32 v138, v152, v137
	v_mov_b32_e32 v141, v139
	v_mov_b32_e32 v140, v138
	s_nop 0
	v_permlane16_swap_b32_e32 v139, v141
	v_permlane16_swap_b32_e32 v138, v140
	v_pk_add_f32 v[138:139], v[138:139], v[140:141]
	v_mov_b32_e32 v146, v155
	v_pk_fma_f32 v[138:139], v[138:139], s[16:17], v[158:159] op_sel_hi:[1,0,0]
	v_mov_b32_e32 v147, v156
	v_mul_f32_e32 v137, 0x4b800000, v139
	v_cmp_gt_f32_e32 vcc, s57, v139
	v_mov_b32_e32 v155, v157
	v_pk_add_f32 v[146:147], v[146:147], v[154:155]
	v_cndmask_b32_e32 v137, v139, v137, vcc
	v_rsq_f32_e32 v139, v137
	v_mul_f32_e32 v137, 0x4b800000, v138
	v_cmp_gt_f32_e64 s[2:3], s57, v138
	v_mov_b32_e32 v148, v179
	v_mov_b32_e32 v149, v180
	v_mov_b32_e32 v179, v181
	v_pk_add_f32 v[146:147], v[146:147], v[146:147] op_sel:[0,1] op_sel_hi:[1,0]
	v_cndmask_b32_e64 v137, v138, v137, s[2:3]
	v_pk_add_f32 v[148:149], v[148:149], v[178:179]
	v_rsq_f32_e32 v138, v137
	v_mov_b32_e32 v137, v146
	v_pk_add_f32 v[148:149], v[148:149], v[148:149] op_sel:[0,1] op_sel_hi:[1,0]
	s_nop 0
	v_permlane32_swap_b32_e32 v146, v137
	v_add_f32_e32 v141, v146, v137
	v_mov_b32_e32 v137, v148
	s_nop 1
	v_permlane32_swap_b32_e32 v148, v137
	v_add_f32_e32 v140, v148, v137
	v_mov_b32_e32 v143, v141
	v_mov_b32_e32 v142, v140
	s_nop 0
	v_permlane16_swap_b32_e32 v141, v143
	v_permlane16_swap_b32_e32 v140, v142
	v_pk_add_f32 v[140:141], v[140:141], v[142:143]
	v_pk_mul_f32 v[142:143], v[138:139], s[22:23] op_sel_hi:[1,0]
	v_pk_fma_f32 v[140:141], v[140:141], s[16:17], v[158:159] op_sel_hi:[1,0,0]
	v_cndmask_b32_e64 v181, v138, v142, s[2:3]
	v_mul_f32_e32 v137, 0x4b800000, v141
	v_cmp_gt_f32_e64 s[4:5], s57, v141
	v_cmp_gt_f32_e64 s[6:7], s57, v140
	v_cndmask_b32_e32 v180, v139, v143, vcc
	v_cndmask_b32_e64 v137, v141, v137, s[4:5]
	v_rsq_f32_e32 v141, v137
	v_mul_f32_e32 v137, 0x4b800000, v140
	v_cndmask_b32_e64 v137, v140, v137, s[6:7]
	v_rsq_f32_e32 v140, v137
	s_mov_b64 s[2:3], 0
	v_mov_b64_e32 v[184:185], v[182:183]
	v_pk_mul_f32 v[138:139], v[140:141], s[22:23] op_sel_hi:[1,0]
	s_nop 0
	v_cndmask_b32_e64 v179, v140, v138, s[6:7]
	v_cndmask_b32_e64 v178, v141, v139, s[4:5]

;     __device__ __forceinline__ void operator()(const f32x4 (&acc)[2][2][4][2], const Unit& u, int wr, int wc, int fr, int fq) const {
;     ...
;             u32x4 prv[4][2], xbv[4][2];
; #pragma unroll
;             for (int m = 0; m < 4; ++m)
; #pragma unroll
;                 for (int bj = 0; bj < 2; ++bj) { const size_t off = (size_t)(row0 + ai * HALF + m * 16) * DM + col0 + bj * HALF; prv[m][bj] = *(const u32x4*)(PR + off); xbv[m][bj] = *(const u32x4*)(Xb + off); }
; #pragma unroll
;             for (int m = 0; m < 4; ++m) { const int row = row0 + ai * HALF + m * 16; const float r = rs[ai][m];
; #pragma unroll
;                 for (int bj = 0; bj < 2; ++bj) { const size_t off = (size_t)row * DM + col0 + bj * HALF;
;                     const u32x4 pr = prv[m][bj], xb = xbv[m][bj];
;                     const float rl = -LOG2E * r;
;                     const f32x4 t0 = acc[ai][bj][m][0] * rl, t1 = acc[ai][bj][m][1] * rl;
;                     const f32x4 d0 = (f32x4){__builtin_amdgcn_exp2f(t0[0]), __builtin_amdgcn_exp2f(t0[1]), __builtin_amdgcn_exp2f(t0[2]), __builtin_amdgcn_exp2f(t0[3])} + 1.f;
;                     const f32x4 d1 = (f32x4){__builtin_amdgcn_exp2f(t1[0]), __builtin_amdgcn_exp2f(t1[1]), __builtin_amdgcn_exp2f(t1[2]), __builtin_amdgcn_exp2f(t1[3])} + 1.f;
;                     const f32x4 s0 = (f32x4){__builtin_amdgcn_rcpf(d0[0]), __builtin_amdgcn_rcpf(d0[1]), __builtin_amdgcn_rcpf(d0[2]), __builtin_amdgcn_rcpf(d0[3])}, s1 = (f32x4){__builtin_amdgcn_rcpf(d1[0]), __builtin_amdgcn_rcpf(d1[1]), __builtin_amdgcn_rcpf(d1[2]), __builtin_amdgcn_rcpf(d1[3])};
.Lp6x_fast:
	s_waitcnt vmcnt(0)
	v_mbcnt_lo_u32_b32 v252, -1, 0
	v_mbcnt_hi_u32_b32 v252, -1, v252
	v_lshlrev_b32_e32 v252, 4, v252
	v_add_u32_e32 v253, s42, v252
	v_lshl_or_b32 v186, s58, 8, v201
	v_ashrrev_i32_e32 v187, 31, v186
	v_lshlrev_b64 v[134:135], 10, v[134:135]
	v_lshl_add_u64 v[230:231], v[134:135], 0, v[186:187]
	v_lshlrev_b64 v[134:135], 1, v[230:231]
	v_lshl_add_u64 v[136:137], s[20:21], 0, v[134:135]
	v_add_u32_e32 v251, s55, v253
	ds_read_b128 v[206:209], v251
	v_lshl_add_u64 v[136:137], s[8:9], 0, v[134:135]
	v_add_u32_e32 v251, s55, v253
	ds_read_b128 v[210:213], v251 offset:8192
	v_or_b32_e32 v134, 0x100, v134
	v_lshl_add_u64 v[138:139], s[8:9], 0, v[134:135]
	v_lshl_add_u64 v[134:135], s[20:21], 0, v[134:135]
	v_add_u32_e32 v251, s56, v253
	ds_read_b128 v[214:217], v251
	v_add_u32_e32 v251, s56, v253
	ds_read_b128 v[218:221], v251 offset:8192
	v_lshlrev_b64 v[132:133], 10, v[132:133]
	s_waitcnt lgkmcnt(0)
	v_mul_f32_e32 v194, 0xbfb8aa3b, v194
	v_pk_mul_f32 v[120:121], v[120:121], v[194:195] op_sel_hi:[1,0]
	v_lshl_add_u64 v[196:197], v[132:133], 0, v[186:187]
	v_pk_mul_f32 v[126:127], v[126:127], v[194:195] op_sel_hi:[1,0]
	v_exp_f32_e32 v236, v120
	v_exp_f32_e32 v237, v121
	v_lshlrev_b64 v[120:121], 1, v[196:197]
	v_lshlrev_b64 v[128:129], 10, v[128:129]
	v_exp_f32_e32 v234, v126
	v_exp_f32_e32 v235, v127
	v_lshl_add_u64 v[126:127], s[8:9], 0, v[120:121]
	v_lshl_add_u64 v[190:191], v[128:129], 0, v[186:187]
	v_lshl_add_u64 v[128:129], s[20:21], 0, v[120:121]
	v_add_u32_e32 v251, s44, v252
	ds_read_b128 v[222:225], v251
	v_add_u32_e32 v251, s45, v252
	ds_read_b128 v[226:229], v251
	v_lshlrev_b64 v[130:131], 10, v[130:131]
	v_pk_mul_f32 v[124:125], v[124:125], v[194:195] op_sel_hi:[1,0]
	v_pk_mul_f32 v[122:123], v[122:123], v[194:195] op_sel_hi:[1,0]
	v_lshl_add_u64 v[192:193], v[130:131], 0, v[186:187]
	v_exp_f32_e32 v232, v124
	v_exp_f32_e32 v233, v125
	v_exp_f32_e32 v238, v122
	v_exp_f32_e32 v239, v123
	v_lshlrev_b64 v[122:123], 1, v[192:193]
	v_lshlrev_b64 v[124:125], 1, v[190:191]
	v_or_b32_e32 v120, 0x100, v120
	v_lshl_add_u64 v[130:131], s[8:9], 0, v[122:123]
	v_lshl_add_u64 v[132:133], s[20:21], 0, v[122:123]
	v_or_b32_e32 v122, 0x100, v122
	v_lshl_add_u64 v[136:137], s[8:9], 0, v[124:125]
	v_lshl_add_u64 v[134:135], s[20:21], 0, v[124:125]
	v_or_b32_e32 v124, 0x100, v124
	v_lshl_add_u64 v[126:127], s[8:9], 0, v[120:121]
	v_lshl_add_u64 v[120:121], s[20:21], 0, v[120:121]
	v_lshl_add_u64 v[138:139], s[8:9], 0, v[122:123]
	v_lshl_add_u64 v[122:123], s[20:21], 0, v[122:123]
	v_lshl_add_u64 v[240:241], s[8:9], 0, v[124:125]
	v_lshl_add_u64 v[124:125], s[20:21], 0, v[124:125]
	v_add_u32_e32 v251, s46, v252
	ds_read_b128 v[144:147], v251
	v_add_u32_e32 v251, s47, v252
	ds_read_b128 v[148:151], v251
	s_nop 0
	v_add_u32_e32 v251, 0x18000, v253
	ds_read_b128 v[128:131], v251
	s_nop 0
	v_add_u32_e32 v251, 0x18000, v253
	ds_read_b128 v[132:135], v251 offset:8192
	s_nop 0
	v_add_u32_e32 v251, 0x1c000, v253
	ds_read_b128 v[152:155], v251
	v_add_u32_e32 v251, 0x1c000, v253
	ds_read_b128 v[156:159], v251 offset:8192
	s_nop 0
	v_add_u32_e32 v251, s52, v252
	ds_read_b128 v[136:139], v251
	s_nop 0
	v_add_u32_e32 v251, s53, v252
	ds_read_b128 v[140:143], v251
	s_nop 0
	global_load_dwordx4 v[120:123], v[240:241], off
	s_nop 0
	global_load_dwordx4 v[124:127], v[124:125], off
	v_pk_mul_f32 v[118:119], v[118:119], v[194:195] op_sel_hi:[1,0]
	v_pk_mul_f32 v[116:117], v[116:117], v[194:195] op_sel_hi:[1,0]
	v_pk_add_f32 v[234:235], v[234:235], 1.0 op_sel_hi:[1,0]
	v_pk_add_f32 v[232:233], v[232:233], 1.0 op_sel_hi:[1,0]
	v_pk_mul_f32 v[114:115], v[114:115], v[194:195] op_sel_hi:[1,0]
	v_pk_mul_f32 v[112:113], v[112:113], v[194:195] op_sel_hi:[1,0]
	v_exp_f32_e32 v116, v116
	v_exp_f32_e32 v117, v117
	v_exp_f32_e32 v118, v118
	v_exp_f32_e32 v119, v119
	v_pk_add_f32 v[238:239], v[238:239], 1.0 op_sel_hi:[1,0]
	v_pk_add_f32 v[236:237], v[236:237], 1.0 op_sel_hi:[1,0]
	v_rcp_f32_e32 v232, v232
	v_rcp_f32_e32 v233, v233
	v_rcp_f32_e32 v234, v234
	v_rcp_f32_e32 v235, v235
	v_exp_f32_e32 v112, v112
	v_exp_f32_e32 v114, v114
	v_exp_f32_e32 v115, v115
	v_exp_f32_e32 v113, v113
	v_rcp_f32_e32 v236, v236
	v_rcp_f32_e32 v237, v237
	v_rcp_f32_e32 v238, v238
	v_rcp_f32_e32 v239, v239
	v_pk_add_f32 v[118:119], v[118:119], 1.0 op_sel_hi:[1,0]
	v_pk_add_f32 v[116:117], v[116:117], 1.0 op_sel_hi:[1,0]
	v_lshl_add_u64 v[230:231], v[230:231], 2, s[50:51]
	v_pk_add_f32 v[114:115], v[114:115], 1.0 op_sel_hi:[1,0]
	v_pk_add_f32 v[112:113], v[112:113], 1.0 op_sel_hi:[1,0]
	v_rcp_f32_e32 v116, v116
	v_rcp_f32_e32 v117, v117
	v_rcp_f32_e32 v118, v118
	s_waitcnt lgkmcnt(0)
	s_add_i32 m0, s55, s42
	s_add_u32 s84, s20, 0x40000
	s_addc_u32 s85, s21, 0
	global_load_lds_dwordx4 v250, s[84:85]
	s_add_i32 s86, s55, s42
	s_add_i32 m0, s86, 0x2000
	s_add_u32 s84, s8, 0x40000
	s_addc_u32 s85, s9, 0
	global_load_lds_dwordx4 v250, s[84:85]
	s_add_i32 m0, s56, s42
	s_add_u32 s84, s8, 0x40100
	s_addc_u32 s85, s9, 0
	global_load_lds_dwordx4 v250, s[84:85]
	s_add_i32 s86, s56, s42
	s_add_i32 m0, s86, 0x2000
	s_add_u32 s84, s20, 0x40100
	s_addc_u32 s85, s21, 0
	global_load_lds_dwordx4 v250, s[84:85]
	s_mov_b32 m0, s44
	s_add_u32 s84, s8, 0x48000
	s_addc_u32 s85, s9, 0
	global_load_lds_dwordx4 v250, s[84:85]
	s_mov_b32 m0, s45
	s_add_u32 s84, s20, 0x48000
	s_addc_u32 s85, s21, 0
	global_load_lds_dwordx4 v250, s[84:85]
	s_mov_b32 m0, s46
	s_add_u32 s84, s8, 0x48100
	s_addc_u32 s85, s9, 0
	global_load_lds_dwordx4 v250, s[84:85]
	s_mov_b32 m0, s47
	s_add_u32 s84, s20, 0x48100
	s_addc_u32 s85, s21, 0
	global_load_lds_dwordx4 v250, s[84:85]
	s_add_i32 m0, s42, 0x18000
	s_add_u32 s84, s8, 0x50000
	s_addc_u32 s85, s9, 0
	global_load_lds_dwordx4 v250, s[84:85]
	s_add_i32 m0, s42, 0x1a000
	s_add_u32 s84, s20, 0x50000
	s_addc_u32 s85, s21, 0
	global_load_lds_dwordx4 v250, s[84:85]
	s_add_i32 m0, s42, 0x1c000
	s_add_u32 s84, s8, 0x50100
	s_addc_u32 s85, s9, 0
	global_load_lds_dwordx4 v250, s[84:85]
	s_add_i32 m0, s42, 0x1e000
	s_add_u32 s84, s20, 0x50100
	s_addc_u32 s85, s21, 0
	global_load_lds_dwordx4 v250, s[84:85]
	s_mov_b32 m0, s52
	s_add_u32 s84, s8, 0x58000
	s_addc_u32 s85, s9, 0
	global_load_lds_dwordx4 v250, s[84:85]
	s_mov_b32 m0, s53
	s_add_u32 s84, s20, 0x58000
	s_addc_u32 s85, s21, 0
	global_load_lds_dwordx4 v250, s[84:85]
	s_add_i32 m0, s44, 0xc000
	s_add_u32 s84, s8, 0x58100
	s_addc_u32 s85, s9, 0
	global_load_lds_dwordx4 v250, s[84:85]
	s_add_i32 m0, s44, 0xe000
	s_add_u32 s84, s20, 0x58100
	s_addc_u32 s85, s21, 0
	global_load_lds_dwordx4 v250, s[84:85]
;     __device__ __forceinline__ void operator()(const f32x4 (&acc)[2][2][4][2], const Unit& u, int wr, int wc, int fr, int fq) const {
;     ...
;             for (int m = 0; m < 4; ++m) { const int row = row0 + ai * HALF + m * 16; const float r = rs[ai][m];
; #pragma unroll
;                 for (int bj = 0; bj < 2; ++bj) { const size_t off = (size_t)row * DM + col0 + bj * HALF;
;                     const u32x4 pr = prv[m][bj], xb = xbv[m][bj];
;                     const float rl = -LOG2E * r;
;                     const f32x4 t0 = acc[ai][bj][m][0] * rl, t1 = acc[ai][bj][m][1] * rl;
;                     const f32x4 d0 = (f32x4){__builtin_amdgcn_exp2f(t0[0]), __builtin_amdgcn_exp2f(t0[1]), __builtin_amdgcn_exp2f(t0[2]), __builtin_amdgcn_exp2f(t0[3])} + 1.f;
;                     const f32x4 d1 = (f32x4){__builtin_amdgcn_exp2f(t1[0]), __builtin_amdgcn_exp2f(t1[1]), __builtin_amdgcn_exp2f(t1[2]), __builtin_amdgcn_exp2f(t1[3])} + 1.f;
;                     const f32x4 s0 = (f32x4){__builtin_amdgcn_rcpf(d0[0]), __builtin_amdgcn_rcpf(d0[1]), __builtin_amdgcn_rcpf(d0[2]), __builtin_amdgcn_rcpf(d0[3])}, s1 = (f32x4){__builtin_amdgcn_rcpf(d1[0]), __builtin_amdgcn_rcpf(d1[1]), __builtin_amdgcn_rcpf(d1[2]), __builtin_amdgcn_rcpf(d1[3])};
;                     const f32x4 x0 = (f32x4){__builtin_bit_cast(float, xb.x << 16), __builtin_bit_cast(float, xb.x & 0xffff0000u), __builtin_bit_cast(float, xb.y << 16), __builtin_bit_cast(float, xb.y & 0xffff0000u)};
;                     const f32x4 x1 = (f32x4){__builtin_bit_cast(float, xb.z << 16), __builtin_bit_cast(float, xb.z & 0xffff0000u), __builtin_bit_cast(float, xb.w << 16), __builtin_bit_cast(float, xb.w & 0xffff0000u)};
;                     const f32x4 p0 = (f32x4){__builtin_bit_cast(float, pr.x << 16), __builtin_bit_cast(float, pr.x & 0xffff0000u), __builtin_bit_cast(float, pr.y << 16), __builtin_bit_cast(float, pr.y & 0xffff0000u)};
;                     const f32x4 p1 = (f32x4){__builtin_bit_cast(float, pr.z << 16), __builtin_bit_cast(float, pr.z & 0xffff0000u), __builtin_bit_cast(float, pr.w << 16), __builtin_bit_cast(float, pr.w & 0xffff0000u)};
;                     const f32x4 o0 = s0 * p0 + x0, o1 = s1 * p1 + x1;
;                     __builtin_nontemporal_store(o0, (f32x4*)(out + off)); __builtin_nontemporal_store(o1, (f32x4*)(out + off + 4)); } }
.Lp6x_join:
	v_lshlrev_b32_e32 v240, 16, v206
	v_and_b32_e32 v241, 0xffff0000, v206
	v_lshlrev_b32_e32 v206, 16, v207
	v_and_b32_e32 v207, 0xffff0000, v207
	v_lshlrev_b32_e32 v242, 16, v208
	v_and_b32_e32 v243, 0xffff0000, v208
	v_lshlrev_b32_e32 v244, 16, v209
	v_and_b32_e32 v245, 0xffff0000, v209
	v_lshlrev_b32_e32 v246, 16, v210
	v_and_b32_e32 v247, 0xffff0000, v210
	v_lshlrev_b32_e32 v208, 16, v211
	v_and_b32_e32 v209, 0xffff0000, v211
	v_lshlrev_b32_e32 v210, 16, v212
	v_and_b32_e32 v211, 0xffff0000, v212
	v_lshlrev_b32_e32 v212, 16, v213
	v_and_b32_e32 v213, 0xffff0000, v213
	v_pk_fma_f32 v[208:209], v[234:235], v[208:209], v[206:207]
	v_pk_fma_f32 v[206:207], v[232:233], v[246:247], v[240:241]
	v_rcp_f32_e32 v119, v119
	v_pk_fma_f32 v[212:213], v[238:239], v[212:213], v[244:245]
	v_pk_fma_f32 v[210:211], v[236:237], v[210:211], v[242:243]
	global_store_dwordx4 v[230:231], v[206:209], off nt
	global_store_dwordx4 v[230:231], v[210:213], off offset:16 nt
	v_lshlrev_b32_e32 v194, 16, v229
	v_rcp_f32_e32 v206, v112
	v_rcp_f32_e32 v207, v113
	v_rcp_f32_e32 v208, v114
	v_rcp_f32_e32 v209, v115
	v_lshlrev_b32_e32 v112, 16, v218
	v_and_b32_e32 v113, 0xffff0000, v218
	v_lshlrev_b32_e32 v114, 16, v219
	v_and_b32_e32 v115, 0xffff0000, v219
	v_lshlrev_b32_e32 v218, 16, v214
	v_and_b32_e32 v219, 0xffff0000, v214
	v_lshlrev_b32_e32 v214, 16, v215
	v_and_b32_e32 v215, 0xffff0000, v215
	v_lshlrev_b32_e32 v210, 16, v220
	v_and_b32_e32 v211, 0xffff0000, v220
	v_lshlrev_b32_e32 v212, 16, v221
	v_and_b32_e32 v213, 0xffff0000, v221
	v_lshlrev_b32_e32 v220, 16, v216
	v_and_b32_e32 v221, 0xffff0000, v216
	v_lshlrev_b32_e32 v216, 16, v217
	v_and_b32_e32 v217, 0xffff0000, v217
	v_pk_fma_f32 v[114:115], v[118:119], v[214:215], v[114:115]
	v_pk_fma_f32 v[112:113], v[116:117], v[218:219], v[112:113]
	v_pk_fma_f32 v[118:119], v[208:209], v[216:217], v[212:213]
	v_pk_fma_f32 v[116:117], v[206:207], v[220:221], v[210:211]
	global_store_dwordx4 v[230:231], v[112:115], off offset:512 nt
	global_store_dwordx4 v[230:231], v[116:119], off offset:528 nt
	v_lshlrev_b32_e32 v206, 16, v222
	v_mul_f32_e32 v112, 0xbfb8aa3b, v195
	v_pk_mul_f32 v[110:111], v[110:111], v[112:113] op_sel_hi:[1,0]
	v_pk_mul_f32 v[108:109], v[108:109], v[112:113] op_sel_hi:[1,0]
	v_pk_mul_f32 v[104:105], v[104:105], v[112:113] op_sel_hi:[1,0]
	v_pk_mul_f32 v[106:107], v[106:107], v[112:113] op_sel_hi:[1,0]
	v_exp_f32_e32 v108, v108
	v_exp_f32_e32 v109, v109
	v_exp_f32_e32 v110, v110
	v_exp_f32_e32 v111, v111
	v_exp_f32_e32 v104, v104
	v_exp_f32_e32 v105, v105
	v_exp_f32_e32 v106, v106
	v_exp_f32_e32 v107, v107
	v_pk_mul_f32 v[102:103], v[102:103], v[112:113] op_sel_hi:[1,0]
	v_pk_mul_f32 v[100:101], v[100:101], v[112:113] op_sel_hi:[1,0]
	v_pk_add_f32 v[110:111], v[110:111], 1.0 op_sel_hi:[1,0]
	v_pk_add_f32 v[108:109], v[108:109], 1.0 op_sel_hi:[1,0]
	v_pk_add_f32 v[104:105], v[104:105], 1.0 op_sel_hi:[1,0]
	v_pk_mul_f32 v[98:99], v[98:99], v[112:113] op_sel_hi:[1,0]
	v_pk_mul_f32 v[96:97], v[96:97], v[112:113] op_sel_hi:[1,0]
	v_exp_f32_e32 v100, v100
	v_exp_f32_e32 v101, v101
	v_exp_f32_e32 v102, v102
	v_exp_f32_e32 v103, v103
	v_pk_add_f32 v[106:107], v[106:107], 1.0 op_sel_hi:[1,0]
	v_rcp_f32_e32 v108, v108
	v_rcp_f32_e32 v109, v109
	v_rcp_f32_e32 v110, v110
	v_rcp_f32_e32 v111, v111
	v_rcp_f32_e32 v114, v104
	v_rcp_f32_e32 v115, v105
	v_exp_f32_e32 v96, v96
	v_exp_f32_e32 v98, v98
	v_exp_f32_e32 v99, v99
	v_exp_f32_e32 v97, v97
	v_rcp_f32_e32 v116, v106
	v_rcp_f32_e32 v117, v107
	v_lshlrev_b32_e32 v104, 16, v226
	v_and_b32_e32 v105, 0xffff0000, v226
	v_lshlrev_b32_e32 v106, 16, v227
	v_and_b32_e32 v107, 0xffff0000, v227
	v_lshlrev_b32_e32 v118, 16, v228
	v_and_b32_e32 v119, 0xffff0000, v228
	v_and_b32_e32 v207, 0xffff0000, v222
	v_lshlrev_b32_e32 v208, 16, v223
	v_and_b32_e32 v209, 0xffff0000, v223
	v_lshlrev_b32_e32 v210, 16, v224
	v_and_b32_e32 v211, 0xffff0000, v224
	v_pk_add_f32 v[102:103], v[102:103], 1.0 op_sel_hi:[1,0]
	v_pk_add_f32 v[100:101], v[100:101], 1.0 op_sel_hi:[1,0]
	v_and_b32_e32 v195, 0xffff0000, v229
	v_lshlrev_b32_e32 v212, 16, v225
	v_and_b32_e32 v213, 0xffff0000, v225
	v_pk_fma_f32 v[106:107], v[110:111], v[208:209], v[106:107]
	v_pk_fma_f32 v[104:105], v[108:109], v[206:207], v[104:105]
	v_pk_fma_f32 v[108:109], v[114:115], v[210:211], v[118:119]
	v_lshl_add_u64 v[114:115], v[196:197], 2, s[50:51]
	v_pk_add_f32 v[98:99], v[98:99], 1.0 op_sel_hi:[1,0]
	v_pk_add_f32 v[96:97], v[96:97], 1.0 op_sel_hi:[1,0]
	v_rcp_f32_e32 v100, v100
	v_rcp_f32_e32 v101, v101
	v_rcp_f32_e32 v102, v102
	v_rcp_f32_e32 v103, v103
	v_pk_fma_f32 v[110:111], v[116:117], v[212:213], v[194:195]
	global_store_dwordx4 v[114:115], v[104:107], off nt
	global_store_dwordx4 v[114:115], v[108:111], off offset:16 nt
	v_lshlrev_b32_e32 v112, 16, v152
	v_rcp_f32_e32 v104, v96
	v_rcp_f32_e32 v105, v97
	v_rcp_f32_e32 v106, v98
	v_rcp_f32_e32 v107, v99
	v_lshlrev_b32_e32 v96, 16, v156
	v_and_b32_e32 v97, 0xffff0000, v156
	v_lshlrev_b32_e32 v98, 16, v157
	v_and_b32_e32 v99, 0xffff0000, v157
	v_and_b32_e32 v113, 0xffff0000, v152
	v_lshlrev_b32_e32 v116, 16, v153
	v_and_b32_e32 v117, 0xffff0000, v153
	v_lshlrev_b32_e32 v108, 16, v158
	v_and_b32_e32 v109, 0xffff0000, v158
	v_lshlrev_b32_e32 v110, 16, v159
	v_and_b32_e32 v111, 0xffff0000, v159
	v_lshlrev_b32_e32 v118, 16, v154
	v_and_b32_e32 v119, 0xffff0000, v154
	v_lshlrev_b32_e32 v152, 16, v155
	v_and_b32_e32 v153, 0xffff0000, v155
	v_pk_fma_f32 v[98:99], v[102:103], v[116:117], v[98:99]
	v_pk_fma_f32 v[96:97], v[100:101], v[112:113], v[96:97]
	v_pk_fma_f32 v[102:103], v[106:107], v[152:153], v[110:111]
	v_pk_fma_f32 v[100:101], v[104:105], v[118:119], v[108:109]
;     __device__ __forceinline__ void operator()(const f32x4 (&acc)[2][2][4][2], const Unit& u, int wr, int wc, int fr, int fq) const {
;     ...
;             for (int m = 0; m < 4; ++m) { const int row = row0 + ai * HALF + m * 16; const float r = rs[ai][m];
; #pragma unroll
;                 for (int bj = 0; bj < 2; ++bj) { const size_t off = (size_t)row * DM + col0 + bj * HALF;
;                     const u32x4 pr = prv[m][bj], xb = xbv[m][bj];
;                     const float rl = -LOG2E * r;
;                     const f32x4 t0 = acc[ai][bj][m][0] * rl, t1 = acc[ai][bj][m][1] * rl;
;                     const f32x4 d0 = (f32x4){__builtin_amdgcn_exp2f(t0[0]), __builtin_amdgcn_exp2f(t0[1]), __builtin_amdgcn_exp2f(t0[2]), __builtin_amdgcn_exp2f(t0[3])} + 1.f;
;                     const f32x4 d1 = (f32x4){__builtin_amdgcn_exp2f(t1[0]), __builtin_amdgcn_exp2f(t1[1]), __builtin_amdgcn_exp2f(t1[2]), __builtin_amdgcn_exp2f(t1[3])} + 1.f;
;                     const f32x4 s0 = (f32x4){__builtin_amdgcn_rcpf(d0[0]), __builtin_amdgcn_rcpf(d0[1]), __builtin_amdgcn_rcpf(d0[2]), __builtin_amdgcn_rcpf(d0[3])}, s1 = (f32x4){__builtin_amdgcn_rcpf(d1[0]), __builtin_amdgcn_rcpf(d1[1]), __builtin_amdgcn_rcpf(d1[2]), __builtin_amdgcn_rcpf(d1[3])};
;                     const f32x4 x0 = (f32x4){__builtin_bit_cast(float, xb.x << 16), __builtin_bit_cast(float, xb.x & 0xffff0000u), __builtin_bit_cast(float, xb.y << 16), __builtin_bit_cast(float, xb.y & 0xffff0000u)};
;                     const f32x4 x1 = (f32x4){__builtin_bit_cast(float, xb.z << 16), __builtin_bit_cast(float, xb.z & 0xffff0000u), __builtin_bit_cast(float, xb.w << 16), __builtin_bit_cast(float, xb.w & 0xffff0000u)};
;                     const f32x4 p0 = (f32x4){__builtin_bit_cast(float, pr.x << 16), __builtin_bit_cast(float, pr.x & 0xffff0000u), __builtin_bit_cast(float, pr.y << 16), __builtin_bit_cast(float, pr.y & 0xffff0000u)};
;                     const f32x4 p1 = (f32x4){__builtin_bit_cast(float, pr.z << 16), __builtin_bit_cast(float, pr.z & 0xffff0000u), __builtin_bit_cast(float, pr.w << 16), __builtin_bit_cast(float, pr.w & 0xffff0000u)};
;                     const f32x4 o0 = s0 * p0 + x0, o1 = s1 * p1 + x1;
;                     __builtin_nontemporal_store(o0, (f32x4*)(out + off)); __builtin_nontemporal_store(o1, (f32x4*)(out + off + 4)); } }
	global_store_dwordx4 v[114:115], v[96:99], off offset:512 nt
	global_store_dwordx4 v[114:115], v[100:103], off offset:528 nt
	v_lshlrev_b32_e32 v106, 16, v144
	v_mul_f32_e32 v96, 0xbfb8aa3b, v188
	v_pk_mul_f32 v[94:95], v[94:95], v[96:97] op_sel_hi:[1,0]
	v_pk_mul_f32 v[92:93], v[92:93], v[96:97] op_sel_hi:[1,0]
	v_pk_mul_f32 v[88:89], v[88:89], v[96:97] op_sel_hi:[1,0]
	v_pk_mul_f32 v[90:91], v[90:91], v[96:97] op_sel_hi:[1,0]
	v_exp_f32_e32 v92, v92
	v_exp_f32_e32 v93, v93
	v_exp_f32_e32 v94, v94
	v_exp_f32_e32 v95, v95
	v_exp_f32_e32 v88, v88
	v_exp_f32_e32 v89, v89
	v_exp_f32_e32 v90, v90
	v_exp_f32_e32 v91, v91
	v_pk_mul_f32 v[86:87], v[86:87], v[96:97] op_sel_hi:[1,0]
	v_pk_mul_f32 v[84:85], v[84:85], v[96:97] op_sel_hi:[1,0]
	v_pk_add_f32 v[94:95], v[94:95], 1.0 op_sel_hi:[1,0]
	v_pk_add_f32 v[92:93], v[92:93], 1.0 op_sel_hi:[1,0]
	v_pk_add_f32 v[88:89], v[88:89], 1.0 op_sel_hi:[1,0]
	v_pk_mul_f32 v[82:83], v[82:83], v[96:97] op_sel_hi:[1,0]
	v_pk_mul_f32 v[80:81], v[80:81], v[96:97] op_sel_hi:[1,0]
	v_exp_f32_e32 v84, v84
	v_exp_f32_e32 v85, v85
	v_exp_f32_e32 v86, v86
	v_exp_f32_e32 v87, v87
	v_pk_add_f32 v[90:91], v[90:91], 1.0 op_sel_hi:[1,0]
	v_rcp_f32_e32 v92, v92
	v_rcp_f32_e32 v93, v93
	v_rcp_f32_e32 v94, v94
	v_rcp_f32_e32 v95, v95
	v_rcp_f32_e32 v98, v88
	v_rcp_f32_e32 v99, v89
	v_exp_f32_e32 v80, v80
	v_exp_f32_e32 v82, v82
	v_exp_f32_e32 v83, v83
	v_exp_f32_e32 v81, v81
	v_rcp_f32_e32 v100, v90
	v_rcp_f32_e32 v101, v91
	v_lshlrev_b32_e32 v88, 16, v148
	v_and_b32_e32 v89, 0xffff0000, v148
	v_lshlrev_b32_e32 v90, 16, v149
	v_and_b32_e32 v91, 0xffff0000, v149
	v_lshlrev_b32_e32 v102, 16, v150
	v_and_b32_e32 v103, 0xffff0000, v150
	v_and_b32_e32 v107, 0xffff0000, v144
	v_lshlrev_b32_e32 v108, 16, v145
	v_and_b32_e32 v109, 0xffff0000, v145
	v_lshlrev_b32_e32 v110, 16, v146
	v_and_b32_e32 v111, 0xffff0000, v146
	v_pk_add_f32 v[86:87], v[86:87], 1.0 op_sel_hi:[1,0]
	v_pk_add_f32 v[84:85], v[84:85], 1.0 op_sel_hi:[1,0]
	v_lshlrev_b32_e32 v104, 16, v151
	v_and_b32_e32 v105, 0xffff0000, v151
	v_lshlrev_b32_e32 v112, 16, v147
	v_and_b32_e32 v113, 0xffff0000, v147
	v_pk_fma_f32 v[90:91], v[94:95], v[108:109], v[90:91]
	v_pk_fma_f32 v[88:89], v[92:93], v[106:107], v[88:89]
	v_pk_fma_f32 v[92:93], v[98:99], v[110:111], v[102:103]
	v_lshl_add_u64 v[98:99], v[192:193], 2, s[50:51]
	v_pk_add_f32 v[82:83], v[82:83], 1.0 op_sel_hi:[1,0]
	v_pk_add_f32 v[80:81], v[80:81], 1.0 op_sel_hi:[1,0]
	v_rcp_f32_e32 v84, v84
	v_rcp_f32_e32 v85, v85
	v_rcp_f32_e32 v86, v86
	v_rcp_f32_e32 v87, v87
	v_pk_fma_f32 v[94:95], v[100:101], v[112:113], v[104:105]
	global_store_dwordx4 v[98:99], v[88:91], off nt
	global_store_dwordx4 v[98:99], v[92:95], off offset:16 nt
	v_lshlrev_b32_e32 v96, 16, v136
	v_rcp_f32_e32 v88, v80
	v_rcp_f32_e32 v89, v81
	v_rcp_f32_e32 v90, v82
	v_rcp_f32_e32 v91, v83
	v_lshlrev_b32_e32 v80, 16, v140
	v_and_b32_e32 v81, 0xffff0000, v140
	v_lshlrev_b32_e32 v82, 16, v141
	v_and_b32_e32 v83, 0xffff0000, v141
	v_and_b32_e32 v97, 0xffff0000, v136
	v_lshlrev_b32_e32 v100, 16, v137
	v_and_b32_e32 v101, 0xffff0000, v137
	v_lshlrev_b32_e32 v92, 16, v142
	v_and_b32_e32 v93, 0xffff0000, v142
	v_lshlrev_b32_e32 v94, 16, v143
	v_and_b32_e32 v95, 0xffff0000, v143
	v_lshlrev_b32_e32 v102, 16, v138
	v_and_b32_e32 v103, 0xffff0000, v138
	v_lshlrev_b32_e32 v104, 16, v139
	v_and_b32_e32 v105, 0xffff0000, v139
	v_pk_fma_f32 v[82:83], v[86:87], v[100:101], v[82:83]
	v_pk_fma_f32 v[80:81], v[84:85], v[96:97], v[80:81]
	v_pk_fma_f32 v[86:87], v[90:91], v[104:105], v[94:95]
	v_pk_fma_f32 v[84:85], v[88:89], v[102:103], v[92:93]
	global_store_dwordx4 v[98:99], v[80:83], off offset:512 nt
	global_store_dwordx4 v[98:99], v[84:87], off offset:528 nt
	v_lshlrev_b32_e32 v90, 16, v128
	v_mul_f32_e32 v80, 0xbfb8aa3b, v189
	v_pk_mul_f32 v[78:79], v[78:79], v[80:81] op_sel_hi:[1,0]
	v_pk_mul_f32 v[76:77], v[76:77], v[80:81] op_sel_hi:[1,0]
	v_pk_mul_f32 v[72:73], v[72:73], v[80:81] op_sel_hi:[1,0]
	v_pk_mul_f32 v[74:75], v[74:75], v[80:81] op_sel_hi:[1,0]
	v_exp_f32_e32 v76, v76
	v_exp_f32_e32 v77, v77
	v_exp_f32_e32 v78, v78
	v_exp_f32_e32 v79, v79
	v_exp_f32_e32 v72, v72
	v_exp_f32_e32 v73, v73
	v_exp_f32_e32 v74, v74
	v_exp_f32_e32 v75, v75
	v_pk_mul_f32 v[70:71], v[70:71], v[80:81] op_sel_hi:[1,0]
	v_pk_mul_f32 v[68:69], v[68:69], v[80:81] op_sel_hi:[1,0]
	v_pk_add_f32 v[78:79], v[78:79], 1.0 op_sel_hi:[1,0]
	v_pk_add_f32 v[76:77], v[76:77], 1.0 op_sel_hi:[1,0]
	v_pk_add_f32 v[72:73], v[72:73], 1.0 op_sel_hi:[1,0]
	v_pk_mul_f32 v[66:67], v[66:67], v[80:81] op_sel_hi:[1,0]
	v_pk_mul_f32 v[64:65], v[64:65], v[80:81] op_sel_hi:[1,0]
	v_exp_f32_e32 v68, v68
	v_exp_f32_e32 v69, v69
	v_exp_f32_e32 v70, v70
	v_exp_f32_e32 v71, v71
	v_pk_add_f32 v[74:75], v[74:75], 1.0 op_sel_hi:[1,0]
	v_rcp_f32_e32 v76, v76
	v_rcp_f32_e32 v77, v77
	v_rcp_f32_e32 v78, v78
	v_rcp_f32_e32 v79, v79
	v_rcp_f32_e32 v82, v72
	v_rcp_f32_e32 v83, v73
	v_exp_f32_e32 v64, v64
	v_exp_f32_e32 v66, v66
	v_exp_f32_e32 v67, v67
	v_exp_f32_e32 v65, v65
	v_rcp_f32_e32 v84, v74
	v_rcp_f32_e32 v85, v75
	v_lshlrev_b32_e32 v72, 16, v132
	v_and_b32_e32 v73, 0xffff0000, v132
	v_lshlrev_b32_e32 v74, 16, v133
	v_and_b32_e32 v75, 0xffff0000, v133
	v_lshlrev_b32_e32 v86, 16, v134
	v_and_b32_e32 v87, 0xffff0000, v134
	v_and_b32_e32 v91, 0xffff0000, v128
	v_lshlrev_b32_e32 v92, 16, v129
	v_and_b32_e32 v93, 0xffff0000, v129
	v_lshlrev_b32_e32 v94, 16, v130
	v_and_b32_e32 v95, 0xffff0000, v130
	v_pk_add_f32 v[70:71], v[70:71], 1.0 op_sel_hi:[1,0]
	v_pk_add_f32 v[68:69], v[68:69], 1.0 op_sel_hi:[1,0]
	v_lshlrev_b32_e32 v88, 16, v135
	v_and_b32_e32 v89, 0xffff0000, v135
	v_lshlrev_b32_e32 v96, 16, v131
	v_and_b32_e32 v97, 0xffff0000, v131
	v_pk_fma_f32 v[74:75], v[78:79], v[92:93], v[74:75]
	v_pk_fma_f32 v[72:73], v[76:77], v[90:91], v[72:73]
	v_pk_fma_f32 v[76:77], v[82:83], v[94:95], v[86:87]
	v_lshl_add_u64 v[82:83], v[190:191], 2, s[50:51]
	v_pk_add_f32 v[66:67], v[66:67], 1.0 op_sel_hi:[1,0]
	v_pk_add_f32 v[64:65], v[64:65], 1.0 op_sel_hi:[1,0]
	v_rcp_f32_e32 v68, v68
	v_rcp_f32_e32 v69, v69
	v_rcp_f32_e32 v70, v70
	v_rcp_f32_e32 v71, v71
	v_pk_fma_f32 v[78:79], v[84:85], v[96:97], v[88:89]
	global_store_dwordx4 v[82:83], v[72:75], off nt
	global_store_dwordx4 v[82:83], v[76:79], off offset:16 nt
	s_waitcnt vmcnt(30)
;     __device__ __forceinline__ void operator()(const f32x4 (&acc)[2][2][4][2], const Unit& u, int wr, int wc, int fr, int fq) const {
;     ...
;             u32x4 prv[4][2], xbv[4][2];
; #pragma unroll
;             for (int m = 0; m < 4; ++m)
; #pragma unroll
;                 for (int bj = 0; bj < 2; ++bj) { const size_t off = (size_t)(row0 + ai * HALF + m * 16) * DM + col0 + bj * HALF; prv[m][bj] = *(const u32x4*)(PR + off); xbv[m][bj] = *(const u32x4*)(Xb + off); }
;     ...
;                     const f32x4 x0 = (f32x4){__builtin_bit_cast(float, xb.x << 16), __builtin_bit_cast(float, xb.x & 0xffff0000u), __builtin_bit_cast(float, xb.y << 16), __builtin_bit_cast(float, xb.y & 0xffff0000u)};
;                     const f32x4 x1 = (f32x4){__builtin_bit_cast(float, xb.z << 16), __builtin_bit_cast(float, xb.z & 0xffff0000u), __builtin_bit_cast(float, xb.w << 16), __builtin_bit_cast(float, xb.w & 0xffff0000u)};
;                     const f32x4 p0 = (f32x4){__builtin_bit_cast(float, pr.x << 16), __builtin_bit_cast(float, pr.x & 0xffff0000u), __builtin_bit_cast(float, pr.y << 16), __builtin_bit_cast(float, pr.y & 0xffff0000u)};
;                     const f32x4 p1 = (f32x4){__builtin_bit_cast(float, pr.z << 16), __builtin_bit_cast(float, pr.z & 0xffff0000u), __builtin_bit_cast(float, pr.w << 16), __builtin_bit_cast(float, pr.w & 0xffff0000u)};
;                     const f32x4 o0 = s0 * p0 + x0, o1 = s1 * p1 + x1;
;                     __builtin_nontemporal_store(o0, (f32x4*)(out + off)); __builtin_nontemporal_store(o1, (f32x4*)(out + off + 4)); } }
	v_lshlrev_b32_e32 v80, 16, v120
	v_rcp_f32_e32 v72, v64
	v_rcp_f32_e32 v73, v65
	v_rcp_f32_e32 v74, v66
	v_rcp_f32_e32 v75, v67
	v_lshlrev_b32_e32 v64, 16, v124
	v_and_b32_e32 v65, 0xffff0000, v124
	v_lshlrev_b32_e32 v66, 16, v125
	v_and_b32_e32 v67, 0xffff0000, v125
	v_and_b32_e32 v81, 0xffff0000, v120
	v_lshlrev_b32_e32 v84, 16, v121
	v_and_b32_e32 v85, 0xffff0000, v121
	v_lshlrev_b32_e32 v76, 16, v126
	v_and_b32_e32 v77, 0xffff0000, v126
	v_lshlrev_b32_e32 v78, 16, v127
	v_and_b32_e32 v79, 0xffff0000, v127
	v_lshlrev_b32_e32 v86, 16, v122
	v_and_b32_e32 v87, 0xffff0000, v122
	v_lshlrev_b32_e32 v88, 16, v123
	v_and_b32_e32 v89, 0xffff0000, v123
	v_pk_fma_f32 v[66:67], v[70:71], v[84:85], v[66:67]
	v_pk_fma_f32 v[64:65], v[68:69], v[80:81], v[64:65]
	v_pk_fma_f32 v[70:71], v[74:75], v[88:89], v[78:79]
	v_pk_fma_f32 v[68:69], v[72:73], v[86:87], v[76:77]
	global_store_dwordx4 v[82:83], v[64:67], off offset:512 nt
	global_store_dwordx4 v[82:83], v[68:71], off offset:528 nt
	s_cmp_lg_u32 s32, 0
	s_cbranch_scc1 .Lp6x_fast2
	v_ashrrev_i32_e32 v183, 31, v182
	v_lshlrev_b64 v[64:65], 10, v[184:185]
	v_lshl_add_u64 v[134:135], v[64:65], 0, v[186:187]
	v_lshlrev_b64 v[64:65], 1, v[134:135]
	v_lshl_add_u64 v[66:67], s[20:21], 0, v[64:65]
	global_load_dwordx4 v[118:121], v[66:67], off
	v_lshl_add_u64 v[66:67], s[8:9], 0, v[64:65]
	global_load_dwordx4 v[122:125], v[66:67], off
	v_or_b32_e32 v64, 0x100, v64
	v_lshl_add_u64 v[66:67], s[8:9], 0, v[64:65]
	v_lshl_add_u64 v[64:65], s[20:21], 0, v[64:65]
	global_load_dwordx4 v[126:129], v[66:67], off
	global_load_dwordx4 v[130:133], v[64:65], off
	v_lshlrev_b64 v[64:65], 10, v[182:183]
	v_lshl_add_u64 v[64:65], v[64:65], 0, v[186:187]
	v_lshl_add_u64 v[116:117], v[64:65], 0, s[24:25]
	v_lshlrev_b64 v[66:67], 1, v[116:117]
	v_lshl_add_u64 v[68:69], s[8:9], 0, v[66:67]
	v_lshl_add_u64 v[70:71], s[20:21], 0, v[66:67]
	global_load_dwordx4 v[104:107], v[68:69], off
	global_load_dwordx4 v[108:111], v[70:71], off
	v_or_b32_e32 v66, 0x100, v66
	v_lshl_add_u64 v[68:69], s[8:9], 0, v[66:67]
	v_lshl_add_u64 v[66:67], s[20:21], 0, v[66:67]
	global_load_dwordx4 v[96:99], v[68:69], off
	global_load_dwordx4 v[100:103], v[66:67], off
	v_lshl_add_u64 v[114:115], v[64:65], 0, s[26:27]
	v_lshlrev_b64 v[66:67], 1, v[114:115]
	v_lshl_add_u64 v[68:69], s[8:9], 0, v[66:67]
	v_lshl_add_u64 v[70:71], s[20:21], 0, v[66:67]
	global_load_dwordx4 v[88:91], v[68:69], off
	global_load_dwordx4 v[92:95], v[70:71], off
	v_or_b32_e32 v66, 0x100, v66
	v_lshl_add_u64 v[68:69], s[8:9], 0, v[66:67]
	v_lshl_add_u64 v[66:67], s[20:21], 0, v[66:67]
	global_load_dwordx4 v[80:83], v[68:69], off
	global_load_dwordx4 v[84:87], v[66:67], off
	v_lshl_add_u64 v[112:113], v[64:65], 0, s[28:29]
	v_lshlrev_b64 v[64:65], 1, v[112:113]
	v_lshl_add_u64 v[66:67], s[8:9], 0, v[64:65]
	v_lshl_add_u64 v[68:69], s[20:21], 0, v[64:65]
	global_load_dwordx4 v[72:75], v[66:67], off
	global_load_dwordx4 v[76:79], v[68:69], off
	v_or_b32_e32 v64, 0x100, v64
	v_lshl_add_u64 v[66:67], s[8:9], 0, v[64:65]
	v_lshl_add_u64 v[68:69], s[20:21], 0, v[64:65]
	global_load_dwordx4 v[64:67], v[66:67], off
	s_nop 0
	global_load_dwordx4 v[68:71], v[68:69], off
	s_branch .Lp6x_join2
.Lp6x_fast2:
	s_waitcnt vmcnt(16)
	v_ashrrev_i32_e32 v183, 31, v182
	v_lshlrev_b64 v[64:65], 10, v[184:185]
	v_lshl_add_u64 v[134:135], v[64:65], 0, v[186:187]
	v_lshlrev_b64 v[64:65], 1, v[134:135]
	v_lshl_add_u64 v[66:67], s[20:21], 0, v[64:65]
	v_add_u32_e32 v251, s55, v253
	ds_read_b128 v[118:121], v251
	v_lshl_add_u64 v[66:67], s[8:9], 0, v[64:65]
	v_add_u32_e32 v251, s55, v253
	ds_read_b128 v[122:125], v251 offset:8192
	v_or_b32_e32 v64, 0x100, v64
	v_lshl_add_u64 v[66:67], s[8:9], 0, v[64:65]
	v_lshl_add_u64 v[64:65], s[20:21], 0, v[64:65]
	v_add_u32_e32 v251, s56, v253
	ds_read_b128 v[126:129], v251
	v_add_u32_e32 v251, s56, v253
	ds_read_b128 v[130:133], v251 offset:8192
	v_lshlrev_b64 v[64:65], 10, v[182:183]
	v_lshl_add_u64 v[64:65], v[64:65], 0, v[186:187]
	v_lshl_add_u64 v[116:117], v[64:65], 0, s[24:25]
	v_lshlrev_b64 v[66:67], 1, v[116:117]
	v_lshl_add_u64 v[68:69], s[8:9], 0, v[66:67]
	v_lshl_add_u64 v[70:71], s[20:21], 0, v[66:67]
	v_add_u32_e32 v251, s44, v252
	ds_read_b128 v[104:107], v251
	v_add_u32_e32 v251, s45, v252
	ds_read_b128 v[108:111], v251
	v_or_b32_e32 v66, 0x100, v66
	v_lshl_add_u64 v[68:69], s[8:9], 0, v[66:67]
	v_lshl_add_u64 v[66:67], s[20:21], 0, v[66:67]
	v_add_u32_e32 v251, s46, v252
	ds_read_b128 v[96:99], v251
	v_add_u32_e32 v251, s47, v252
	ds_read_b128 v[100:103], v251
	v_lshl_add_u64 v[114:115], v[64:65], 0, s[26:27]
	v_lshlrev_b64 v[66:67], 1, v[114:115]
	v_lshl_add_u64 v[68:69], s[8:9], 0, v[66:67]
	v_lshl_add_u64 v[70:71], s[20:21], 0, v[66:67]
	v_add_u32_e32 v251, 0x18000, v253
	ds_read_b128 v[88:91], v251
	v_add_u32_e32 v251, 0x18000, v253
	ds_read_b128 v[92:95], v251 offset:8192
	v_or_b32_e32 v66, 0x100, v66
	v_lshl_add_u64 v[68:69], s[8:9], 0, v[66:67]
	v_lshl_add_u64 v[66:67], s[20:21], 0, v[66:67]
	v_add_u32_e32 v251, 0x1c000, v253
	ds_read_b128 v[80:83], v251
	v_add_u32_e32 v251, 0x1c000, v253
	ds_read_b128 v[84:87], v251 offset:8192
	v_lshl_add_u64 v[112:113], v[64:65], 0, s[28:29]
	v_lshlrev_b64 v[64:65], 1, v[112:113]
	v_lshl_add_u64 v[66:67], s[8:9], 0, v[64:65]
	v_lshl_add_u64 v[68:69], s[20:21], 0, v[64:65]
	v_add_u32_e32 v251, s52, v252
	ds_read_b128 v[72:75], v251
	v_add_u32_e32 v251, s53, v252
	ds_read_b128 v[76:79], v251
	v_or_b32_e32 v64, 0x100, v64
	v_lshl_add_u64 v[66:67], s[8:9], 0, v[64:65]
	v_lshl_add_u64 v[68:69], s[20:21], 0, v[64:65]
	v_add_u32_e32 v251, s44, v252
	ds_read_b128 v[64:67], v251 offset:49152
	s_nop 0
	v_add_u32_e32 v251, s44, v252
	ds_read_b128 v[68:71], v251 offset:57344
;     __device__ __forceinline__ void operator()(const f32x4 (&acc)[2][2][4][2], const Unit& u, int wr, int wc, int fr, int fq) const {
;     ...
;             for (int m = 0; m < 4; ++m) { const int row = row0 + ai * HALF + m * 16; const float r = rs[ai][m];
; #pragma unroll
;                 for (int bj = 0; bj < 2; ++bj) { const size_t off = (size_t)row * DM + col0 + bj * HALF;
;                     const u32x4 pr = prv[m][bj], xb = xbv[m][bj];
;                     const float rl = -LOG2E * r;
;                     const f32x4 t0 = acc[ai][bj][m][0] * rl, t1 = acc[ai][bj][m][1] * rl;
;                     const f32x4 d0 = (f32x4){__builtin_amdgcn_exp2f(t0[0]), __builtin_amdgcn_exp2f(t0[1]), __builtin_amdgcn_exp2f(t0[2]), __builtin_amdgcn_exp2f(t0[3])} + 1.f;
;                     const f32x4 d1 = (f32x4){__builtin_amdgcn_exp2f(t1[0]), __builtin_amdgcn_exp2f(t1[1]), __builtin_amdgcn_exp2f(t1[2]), __builtin_amdgcn_exp2f(t1[3])} + 1.f;
;                     const f32x4 s0 = (f32x4){__builtin_amdgcn_rcpf(d0[0]), __builtin_amdgcn_rcpf(d0[1]), __builtin_amdgcn_rcpf(d0[2]), __builtin_amdgcn_rcpf(d0[3])}, s1 = (f32x4){__builtin_amdgcn_rcpf(d1[0]), __builtin_amdgcn_rcpf(d1[1]), __builtin_amdgcn_rcpf(d1[2]), __builtin_amdgcn_rcpf(d1[3])};
;                     const f32x4 x0 = (f32x4){__builtin_bit_cast(float, xb.x << 16), __builtin_bit_cast(float, xb.x & 0xffff0000u), __builtin_bit_cast(float, xb.y << 16), __builtin_bit_cast(float, xb.y & 0xffff0000u)};
;                     const f32x4 x1 = (f32x4){__builtin_bit_cast(float, xb.z << 16), __builtin_bit_cast(float, xb.z & 0xffff0000u), __builtin_bit_cast(float, xb.w << 16), __builtin_bit_cast(float, xb.w & 0xffff0000u)};
;                     const f32x4 p0 = (f32x4){__builtin_bit_cast(float, pr.x << 16), __builtin_bit_cast(float, pr.x & 0xffff0000u), __builtin_bit_cast(float, pr.y << 16), __builtin_bit_cast(float, pr.y & 0xffff0000u)};
;                     const f32x4 p1 = (f32x4){__builtin_bit_cast(float, pr.z << 16), __builtin_bit_cast(float, pr.z & 0xffff0000u), __builtin_bit_cast(float, pr.w << 16), __builtin_bit_cast(float, pr.w & 0xffff0000u)};
;                     const f32x4 o0 = s0 * p0 + x0, o1 = s1 * p1 + x1;
;                     __builtin_nontemporal_store(o0, (f32x4*)(out + off)); __builtin_nontemporal_store(o1, (f32x4*)(out + off + 4)); } }
.Lp6x_join2:
	v_mul_f32_e32 v136, 0xbfb8aa3b, v180
	v_pk_mul_f32 v[62:63], v[62:63], v[136:137] op_sel_hi:[1,0]
	v_pk_mul_f32 v[60:61], v[60:61], v[136:137] op_sel_hi:[1,0]
	v_pk_mul_f32 v[56:57], v[56:57], v[136:137] op_sel_hi:[1,0]
	v_pk_mul_f32 v[58:59], v[58:59], v[136:137] op_sel_hi:[1,0]
	v_exp_f32_e32 v60, v60
	v_exp_f32_e32 v61, v61
	v_exp_f32_e32 v62, v62
	v_exp_f32_e32 v63, v63
	v_exp_f32_e32 v56, v56
	v_exp_f32_e32 v57, v57
	v_exp_f32_e32 v58, v58
	v_exp_f32_e32 v59, v59
	v_pk_mul_f32 v[54:55], v[54:55], v[136:137] op_sel_hi:[1,0]
	v_pk_mul_f32 v[52:53], v[52:53], v[136:137] op_sel_hi:[1,0]
	v_pk_add_f32 v[62:63], v[62:63], 1.0 op_sel_hi:[1,0]
	v_pk_add_f32 v[60:61], v[60:61], 1.0 op_sel_hi:[1,0]
	v_pk_add_f32 v[56:57], v[56:57], 1.0 op_sel_hi:[1,0]
	v_pk_mul_f32 v[50:51], v[50:51], v[136:137] op_sel_hi:[1,0]
	v_pk_mul_f32 v[48:49], v[48:49], v[136:137] op_sel_hi:[1,0]
	v_exp_f32_e32 v52, v52
	v_exp_f32_e32 v53, v53
	v_exp_f32_e32 v54, v54
	v_exp_f32_e32 v55, v55
	v_pk_add_f32 v[58:59], v[58:59], 1.0 op_sel_hi:[1,0]
	v_rcp_f32_e32 v60, v60
	v_rcp_f32_e32 v61, v61
	v_rcp_f32_e32 v62, v62
	v_rcp_f32_e32 v63, v63
	v_rcp_f32_e32 v138, v56
	v_rcp_f32_e32 v139, v57
	v_exp_f32_e32 v48, v48
	v_exp_f32_e32 v50, v50
	v_exp_f32_e32 v51, v51
	v_exp_f32_e32 v49, v49
	v_rcp_f32_e32 v140, v58
	v_rcp_f32_e32 v141, v59
	v_pk_add_f32 v[54:55], v[54:55], 1.0 op_sel_hi:[1,0]
	v_pk_add_f32 v[52:53], v[52:53], 1.0 op_sel_hi:[1,0]
	v_pk_add_f32 v[50:51], v[50:51], 1.0 op_sel_hi:[1,0]
	v_pk_add_f32 v[48:49], v[48:49], 1.0 op_sel_hi:[1,0]
	v_rcp_f32_e32 v52, v52
	v_rcp_f32_e32 v53, v53
	v_rcp_f32_e32 v54, v54
	s_waitcnt lgkmcnt(0)
	s_waitcnt vmcnt(15)
	v_lshlrev_b32_e32 v56, 16, v118
	v_and_b32_e32 v57, 0xffff0000, v118
	v_lshlrev_b32_e32 v58, 16, v119
	v_and_b32_e32 v59, 0xffff0000, v119
	v_lshlrev_b32_e32 v118, 16, v120
	v_and_b32_e32 v119, 0xffff0000, v120
	s_waitcnt vmcnt(14)
	v_lshlrev_b32_e32 v142, 16, v122
	v_and_b32_e32 v143, 0xffff0000, v122
	v_lshlrev_b32_e32 v122, 16, v123
	v_and_b32_e32 v123, 0xffff0000, v123
	v_lshlrev_b32_e32 v144, 16, v124
	v_and_b32_e32 v145, 0xffff0000, v124
	v_lshlrev_b32_e32 v120, 16, v121
	v_and_b32_e32 v121, 0xffff0000, v121
	v_lshlrev_b32_e32 v124, 16, v125
	v_and_b32_e32 v125, 0xffff0000, v125
	v_pk_fma_f32 v[58:59], v[62:63], v[122:123], v[58:59]
	v_pk_fma_f32 v[56:57], v[60:61], v[142:143], v[56:57]
	v_pk_fma_f32 v[60:61], v[138:139], v[144:145], v[118:119]
	v_lshl_add_u64 v[118:119], v[134:135], 2, s[50:51]
	v_rcp_f32_e32 v55, v55
	v_pk_fma_f32 v[62:63], v[140:141], v[124:125], v[120:121]
	global_store_dwordx4 v[118:119], v[56:59], off nt
	global_store_dwordx4 v[118:119], v[60:63], off offset:16 nt
	s_waitcnt vmcnt(15)
	v_lshlrev_b32_e32 v120, 16, v126
	v_rcp_f32_e32 v56, v48
	v_rcp_f32_e32 v57, v49
	v_rcp_f32_e32 v58, v50
	v_rcp_f32_e32 v59, v51
	s_waitcnt vmcnt(14)
	v_lshlrev_b32_e32 v48, 16, v130
	v_and_b32_e32 v49, 0xffff0000, v130
	v_lshlrev_b32_e32 v50, 16, v131
	v_and_b32_e32 v51, 0xffff0000, v131
	v_and_b32_e32 v121, 0xffff0000, v126
	v_lshlrev_b32_e32 v122, 16, v127
	v_and_b32_e32 v123, 0xffff0000, v127
	v_lshlrev_b32_e32 v60, 16, v132
	v_and_b32_e32 v61, 0xffff0000, v132
	v_lshlrev_b32_e32 v62, 16, v133
	v_and_b32_e32 v63, 0xffff0000, v133
	v_lshlrev_b32_e32 v124, 16, v128
	v_and_b32_e32 v125, 0xffff0000, v128
	v_lshlrev_b32_e32 v126, 16, v129
	v_and_b32_e32 v127, 0xffff0000, v129
	v_pk_fma_f32 v[50:51], v[54:55], v[122:123], v[50:51]
	v_pk_fma_f32 v[48:49], v[52:53], v[120:121], v[48:49]
	v_pk_fma_f32 v[54:55], v[58:59], v[126:127], v[62:63]
	v_pk_fma_f32 v[52:53], v[56:57], v[124:125], v[60:61]
	global_store_dwordx4 v[118:119], v[48:51], off offset:512 nt
	global_store_dwordx4 v[118:119], v[52:55], off offset:528 nt
	s_waitcnt vmcnt(15)
	v_lshlrev_b32_e32 v58, 16, v104
	v_mul_f32_e32 v48, 0xbfb8aa3b, v181
	v_pk_mul_f32 v[46:47], v[46:47], v[48:49] op_sel_hi:[1,0]
	v_pk_mul_f32 v[44:45], v[44:45], v[48:49] op_sel_hi:[1,0]
	v_pk_mul_f32 v[40:41], v[40:41], v[48:49] op_sel_hi:[1,0]
	v_pk_mul_f32 v[42:43], v[42:43], v[48:49] op_sel_hi:[1,0]
	v_exp_f32_e32 v44, v44
	v_exp_f32_e32 v45, v45
	v_exp_f32_e32 v46, v46
	v_exp_f32_e32 v47, v47
	v_exp_f32_e32 v40, v40
	v_exp_f32_e32 v41, v41
	v_exp_f32_e32 v42, v42
	v_exp_f32_e32 v43, v43
	v_pk_mul_f32 v[38:39], v[38:39], v[48:49] op_sel_hi:[1,0]
	v_pk_mul_f32 v[36:37], v[36:37], v[48:49] op_sel_hi:[1,0]
	v_pk_add_f32 v[46:47], v[46:47], 1.0 op_sel_hi:[1,0]
	v_pk_add_f32 v[44:45], v[44:45], 1.0 op_sel_hi:[1,0]
	v_pk_add_f32 v[40:41], v[40:41], 1.0 op_sel_hi:[1,0]
	v_pk_mul_f32 v[34:35], v[34:35], v[48:49] op_sel_hi:[1,0]
	v_pk_mul_f32 v[32:33], v[32:33], v[48:49] op_sel_hi:[1,0]
	v_exp_f32_e32 v36, v36
	v_exp_f32_e32 v37, v37
	v_exp_f32_e32 v38, v38
	v_exp_f32_e32 v39, v39
	v_pk_add_f32 v[42:43], v[42:43], 1.0 op_sel_hi:[1,0]
	v_rcp_f32_e32 v44, v44
	v_rcp_f32_e32 v45, v45
	v_rcp_f32_e32 v46, v46
	v_rcp_f32_e32 v47, v47
	v_rcp_f32_e32 v50, v40
	v_rcp_f32_e32 v51, v41
	v_exp_f32_e32 v32, v32
	v_exp_f32_e32 v34, v34
	v_exp_f32_e32 v35, v35
	v_exp_f32_e32 v33, v33
	v_rcp_f32_e32 v52, v42
	v_rcp_f32_e32 v53, v43
	s_waitcnt vmcnt(14)
;     __device__ __forceinline__ void operator()(const f32x4 (&acc)[2][2][4][2], const Unit& u, int wr, int wc, int fr, int fq) const {
;     ...
;             for (int m = 0; m < 4; ++m) { const int row = row0 + ai * HALF + m * 16; const float r = rs[ai][m];
; #pragma unroll
;                 for (int bj = 0; bj < 2; ++bj) { const size_t off = (size_t)row * DM + col0 + bj * HALF;
;                     const u32x4 pr = prv[m][bj], xb = xbv[m][bj];
;                     const float rl = -LOG2E * r;
;                     const f32x4 t0 = acc[ai][bj][m][0] * rl, t1 = acc[ai][bj][m][1] * rl;
;                     const f32x4 d0 = (f32x4){__builtin_amdgcn_exp2f(t0[0]), __builtin_amdgcn_exp2f(t0[1]), __builtin_amdgcn_exp2f(t0[2]), __builtin_amdgcn_exp2f(t0[3])} + 1.f;
;                     const f32x4 d1 = (f32x4){__builtin_amdgcn_exp2f(t1[0]), __builtin_amdgcn_exp2f(t1[1]), __builtin_amdgcn_exp2f(t1[2]), __builtin_amdgcn_exp2f(t1[3])} + 1.f;
;                     const f32x4 s0 = (f32x4){__builtin_amdgcn_rcpf(d0[0]), __builtin_amdgcn_rcpf(d0[1]), __builtin_amdgcn_rcpf(d0[2]), __builtin_amdgcn_rcpf(d0[3])}, s1 = (f32x4){__builtin_amdgcn_rcpf(d1[0]), __builtin_amdgcn_rcpf(d1[1]), __builtin_amdgcn_rcpf(d1[2]), __builtin_amdgcn_rcpf(d1[3])};
;                     const f32x4 x0 = (f32x4){__builtin_bit_cast(float, xb.x << 16), __builtin_bit_cast(float, xb.x & 0xffff0000u), __builtin_bit_cast(float, xb.y << 16), __builtin_bit_cast(float, xb.y & 0xffff0000u)};
;                     const f32x4 x1 = (f32x4){__builtin_bit_cast(float, xb.z << 16), __builtin_bit_cast(float, xb.z & 0xffff0000u), __builtin_bit_cast(float, xb.w << 16), __builtin_bit_cast(float, xb.w & 0xffff0000u)};
;                     const f32x4 p0 = (f32x4){__builtin_bit_cast(float, pr.x << 16), __builtin_bit_cast(float, pr.x & 0xffff0000u), __builtin_bit_cast(float, pr.y << 16), __builtin_bit_cast(float, pr.y & 0xffff0000u)};
;                     const f32x4 p1 = (f32x4){__builtin_bit_cast(float, pr.z << 16), __builtin_bit_cast(float, pr.z & 0xffff0000u), __builtin_bit_cast(float, pr.w << 16), __builtin_bit_cast(float, pr.w & 0xffff0000u)};
;                     const f32x4 o0 = s0 * p0 + x0, o1 = s1 * p1 + x1;
;                     __builtin_nontemporal_store(o0, (f32x4*)(out + off)); __builtin_nontemporal_store(o1, (f32x4*)(out + off + 4)); } }
	v_lshlrev_b32_e32 v40, 16, v108
	v_and_b32_e32 v41, 0xffff0000, v108
	v_lshlrev_b32_e32 v42, 16, v109
	v_and_b32_e32 v43, 0xffff0000, v109
	v_lshlrev_b32_e32 v54, 16, v110
	v_and_b32_e32 v55, 0xffff0000, v110
	v_and_b32_e32 v59, 0xffff0000, v104
	v_lshlrev_b32_e32 v60, 16, v105
	v_and_b32_e32 v61, 0xffff0000, v105
	v_lshlrev_b32_e32 v62, 16, v106
	v_and_b32_e32 v63, 0xffff0000, v106
	v_pk_add_f32 v[38:39], v[38:39], 1.0 op_sel_hi:[1,0]
	v_pk_add_f32 v[36:37], v[36:37], 1.0 op_sel_hi:[1,0]
	v_lshlrev_b32_e32 v56, 16, v111
	v_and_b32_e32 v57, 0xffff0000, v111
	v_lshlrev_b32_e32 v104, 16, v107
	v_and_b32_e32 v105, 0xffff0000, v107
	v_pk_fma_f32 v[42:43], v[46:47], v[60:61], v[42:43]
	v_pk_fma_f32 v[40:41], v[44:45], v[58:59], v[40:41]
	v_pk_fma_f32 v[44:45], v[50:51], v[62:63], v[54:55]
	v_lshl_add_u64 v[50:51], v[116:117], 2, s[50:51]
	v_pk_add_f32 v[34:35], v[34:35], 1.0 op_sel_hi:[1,0]
	v_pk_add_f32 v[32:33], v[32:33], 1.0 op_sel_hi:[1,0]
	v_rcp_f32_e32 v36, v36
	v_rcp_f32_e32 v37, v37
	v_rcp_f32_e32 v38, v38
	v_rcp_f32_e32 v39, v39
	v_pk_fma_f32 v[46:47], v[52:53], v[104:105], v[56:57]
	global_store_dwordx4 v[50:51], v[40:43], off nt
	global_store_dwordx4 v[50:51], v[44:47], off offset:16 nt
	s_waitcnt vmcnt(15)
	v_lshlrev_b32_e32 v48, 16, v96
	v_rcp_f32_e32 v40, v32
	v_rcp_f32_e32 v41, v33
	v_rcp_f32_e32 v42, v34
	v_rcp_f32_e32 v43, v35
	s_waitcnt vmcnt(14)
	v_lshlrev_b32_e32 v32, 16, v100
	v_and_b32_e32 v33, 0xffff0000, v100
	v_lshlrev_b32_e32 v34, 16, v101
	v_and_b32_e32 v35, 0xffff0000, v101
	v_and_b32_e32 v49, 0xffff0000, v96
	v_lshlrev_b32_e32 v52, 16, v97
	v_and_b32_e32 v53, 0xffff0000, v97
	v_lshlrev_b32_e32 v44, 16, v102
	v_and_b32_e32 v45, 0xffff0000, v102
	v_lshlrev_b32_e32 v46, 16, v103
	v_and_b32_e32 v47, 0xffff0000, v103
	v_lshlrev_b32_e32 v54, 16, v98
	v_and_b32_e32 v55, 0xffff0000, v98
	v_lshlrev_b32_e32 v56, 16, v99
	v_and_b32_e32 v57, 0xffff0000, v99
	v_pk_fma_f32 v[34:35], v[38:39], v[52:53], v[34:35]
	v_pk_fma_f32 v[32:33], v[36:37], v[48:49], v[32:33]
	v_pk_fma_f32 v[38:39], v[42:43], v[56:57], v[46:47]
	v_pk_fma_f32 v[36:37], v[40:41], v[54:55], v[44:45]
	global_store_dwordx4 v[50:51], v[32:35], off offset:512 nt
	global_store_dwordx4 v[50:51], v[36:39], off offset:528 nt
	s_waitcnt vmcnt(15)
	v_lshlrev_b32_e32 v42, 16, v88
	v_mul_f32_e32 v32, 0xbfb8aa3b, v178
	v_pk_mul_f32 v[30:31], v[30:31], v[32:33] op_sel_hi:[1,0]
	v_pk_mul_f32 v[28:29], v[28:29], v[32:33] op_sel_hi:[1,0]
	v_pk_mul_f32 v[24:25], v[24:25], v[32:33] op_sel_hi:[1,0]
	v_pk_mul_f32 v[26:27], v[26:27], v[32:33] op_sel_hi:[1,0]
	v_exp_f32_e32 v28, v28
	v_exp_f32_e32 v29, v29
	v_exp_f32_e32 v30, v30
	v_exp_f32_e32 v31, v31
	v_exp_f32_e32 v24, v24
	v_exp_f32_e32 v25, v25
	v_exp_f32_e32 v26, v26
	v_exp_f32_e32 v27, v27
	v_pk_mul_f32 v[22:23], v[22:23], v[32:33] op_sel_hi:[1,0]
	v_pk_mul_f32 v[20:21], v[20:21], v[32:33] op_sel_hi:[1,0]
	v_pk_add_f32 v[30:31], v[30:31], 1.0 op_sel_hi:[1,0]
	v_pk_add_f32 v[28:29], v[28:29], 1.0 op_sel_hi:[1,0]
	v_pk_add_f32 v[24:25], v[24:25], 1.0 op_sel_hi:[1,0]
	v_pk_mul_f32 v[18:19], v[18:19], v[32:33] op_sel_hi:[1,0]
	v_pk_mul_f32 v[16:17], v[16:17], v[32:33] op_sel_hi:[1,0]
	v_exp_f32_e32 v20, v20
	v_exp_f32_e32 v21, v21
	v_exp_f32_e32 v22, v22
	v_exp_f32_e32 v23, v23
	v_pk_add_f32 v[26:27], v[26:27], 1.0 op_sel_hi:[1,0]
	v_rcp_f32_e32 v28, v28
	v_rcp_f32_e32 v29, v29
	v_rcp_f32_e32 v30, v30
	v_rcp_f32_e32 v31, v31
	v_rcp_f32_e32 v34, v24
	v_rcp_f32_e32 v35, v25
	v_exp_f32_e32 v16, v16
	v_exp_f32_e32 v18, v18
	v_exp_f32_e32 v19, v19
	v_exp_f32_e32 v17, v17
	v_rcp_f32_e32 v36, v26
	v_rcp_f32_e32 v37, v27
	s_waitcnt vmcnt(14)
	v_lshlrev_b32_e32 v24, 16, v92
	v_and_b32_e32 v25, 0xffff0000, v92
	v_lshlrev_b32_e32 v26, 16, v93
	v_and_b32_e32 v27, 0xffff0000, v93
	v_lshlrev_b32_e32 v38, 16, v94
	v_and_b32_e32 v39, 0xffff0000, v94
	v_and_b32_e32 v43, 0xffff0000, v88
	v_lshlrev_b32_e32 v44, 16, v89
	v_and_b32_e32 v45, 0xffff0000, v89
	v_lshlrev_b32_e32 v46, 16, v90
	v_and_b32_e32 v47, 0xffff0000, v90
	v_pk_add_f32 v[22:23], v[22:23], 1.0 op_sel_hi:[1,0]
	v_pk_add_f32 v[20:21], v[20:21], 1.0 op_sel_hi:[1,0]
	v_lshlrev_b32_e32 v40, 16, v95
	v_and_b32_e32 v41, 0xffff0000, v95
	v_lshlrev_b32_e32 v48, 16, v91
	v_and_b32_e32 v49, 0xffff0000, v91
	v_pk_fma_f32 v[26:27], v[30:31], v[44:45], v[26:27]
	v_pk_fma_f32 v[24:25], v[28:29], v[42:43], v[24:25]
	v_pk_fma_f32 v[28:29], v[34:35], v[46:47], v[38:39]
	v_lshl_add_u64 v[34:35], v[114:115], 2, s[50:51]
	v_pk_add_f32 v[18:19], v[18:19], 1.0 op_sel_hi:[1,0]
	v_pk_add_f32 v[16:17], v[16:17], 1.0 op_sel_hi:[1,0]
	v_rcp_f32_e32 v20, v20
	v_rcp_f32_e32 v21, v21
	v_rcp_f32_e32 v22, v22
	v_rcp_f32_e32 v23, v23
	v_pk_fma_f32 v[30:31], v[36:37], v[48:49], v[40:41]
	global_store_dwordx4 v[34:35], v[24:27], off nt
	global_store_dwordx4 v[34:35], v[28:31], off offset:16 nt
	s_waitcnt vmcnt(15)
;     __device__ __forceinline__ void operator()(const f32x4 (&acc)[2][2][4][2], const Unit& u, int wr, int wc, int fr, int fq) const {
;     ...
;             for (int m = 0; m < 4; ++m) { const int row = row0 + ai * HALF + m * 16; const float r = rs[ai][m];
; #pragma unroll
;                 for (int bj = 0; bj < 2; ++bj) { const size_t off = (size_t)row * DM + col0 + bj * HALF;
;                     const u32x4 pr = prv[m][bj], xb = xbv[m][bj];
;                     const float rl = -LOG2E * r;
;                     const f32x4 t0 = acc[ai][bj][m][0] * rl, t1 = acc[ai][bj][m][1] * rl;
;                     const f32x4 d0 = (f32x4){__builtin_amdgcn_exp2f(t0[0]), __builtin_amdgcn_exp2f(t0[1]), __builtin_amdgcn_exp2f(t0[2]), __builtin_amdgcn_exp2f(t0[3])} + 1.f;
;                     const f32x4 d1 = (f32x4){__builtin_amdgcn_exp2f(t1[0]), __builtin_amdgcn_exp2f(t1[1]), __builtin_amdgcn_exp2f(t1[2]), __builtin_amdgcn_exp2f(t1[3])} + 1.f;
;                     const f32x4 s0 = (f32x4){__builtin_amdgcn_rcpf(d0[0]), __builtin_amdgcn_rcpf(d0[1]), __builtin_amdgcn_rcpf(d0[2]), __builtin_amdgcn_rcpf(d0[3])}, s1 = (f32x4){__builtin_amdgcn_rcpf(d1[0]), __builtin_amdgcn_rcpf(d1[1]), __builtin_amdgcn_rcpf(d1[2]), __builtin_amdgcn_rcpf(d1[3])};
;                     const f32x4 x0 = (f32x4){__builtin_bit_cast(float, xb.x << 16), __builtin_bit_cast(float, xb.x & 0xffff0000u), __builtin_bit_cast(float, xb.y << 16), __builtin_bit_cast(float, xb.y & 0xffff0000u)};
;                     const f32x4 x1 = (f32x4){__builtin_bit_cast(float, xb.z << 16), __builtin_bit_cast(float, xb.z & 0xffff0000u), __builtin_bit_cast(float, xb.w << 16), __builtin_bit_cast(float, xb.w & 0xffff0000u)};
;                     const f32x4 p0 = (f32x4){__builtin_bit_cast(float, pr.x << 16), __builtin_bit_cast(float, pr.x & 0xffff0000u), __builtin_bit_cast(float, pr.y << 16), __builtin_bit_cast(float, pr.y & 0xffff0000u)};
;                     const f32x4 p1 = (f32x4){__builtin_bit_cast(float, pr.z << 16), __builtin_bit_cast(float, pr.z & 0xffff0000u), __builtin_bit_cast(float, pr.w << 16), __builtin_bit_cast(float, pr.w & 0xffff0000u)};
;                     const f32x4 o0 = s0 * p0 + x0, o1 = s1 * p1 + x1;
;                     __builtin_nontemporal_store(o0, (f32x4*)(out + off)); __builtin_nontemporal_store(o1, (f32x4*)(out + off + 4)); } }
	v_lshlrev_b32_e32 v32, 16, v80
	v_rcp_f32_e32 v24, v16
	v_rcp_f32_e32 v25, v17
	v_rcp_f32_e32 v26, v18
	v_rcp_f32_e32 v27, v19
	s_waitcnt vmcnt(14)
	v_lshlrev_b32_e32 v16, 16, v84
	v_and_b32_e32 v17, 0xffff0000, v84
	v_lshlrev_b32_e32 v18, 16, v85
	v_and_b32_e32 v19, 0xffff0000, v85
	v_and_b32_e32 v33, 0xffff0000, v80
	v_lshlrev_b32_e32 v36, 16, v81
	v_and_b32_e32 v37, 0xffff0000, v81
	v_lshlrev_b32_e32 v28, 16, v86
	v_and_b32_e32 v29, 0xffff0000, v86
	v_lshlrev_b32_e32 v30, 16, v87
	v_and_b32_e32 v31, 0xffff0000, v87
	v_lshlrev_b32_e32 v38, 16, v82
	v_and_b32_e32 v39, 0xffff0000, v82
	v_lshlrev_b32_e32 v40, 16, v83
	v_and_b32_e32 v41, 0xffff0000, v83
	v_pk_fma_f32 v[18:19], v[22:23], v[36:37], v[18:19]
	v_pk_fma_f32 v[16:17], v[20:21], v[32:33], v[16:17]
	v_pk_fma_f32 v[22:23], v[26:27], v[40:41], v[30:31]
	v_pk_fma_f32 v[20:21], v[24:25], v[38:39], v[28:29]
	global_store_dwordx4 v[34:35], v[16:19], off offset:512 nt
	global_store_dwordx4 v[34:35], v[20:23], off offset:528 nt
	s_waitcnt vmcnt(15)
	v_lshlrev_b32_e32 v26, 16, v72
	v_mul_f32_e32 v16, 0xbfb8aa3b, v179
	v_pk_mul_f32 v[14:15], v[14:15], v[16:17] op_sel_hi:[1,0]
	v_pk_mul_f32 v[12:13], v[12:13], v[16:17] op_sel_hi:[1,0]
	v_pk_mul_f32 v[8:9], v[8:9], v[16:17] op_sel_hi:[1,0]
	v_pk_mul_f32 v[10:11], v[10:11], v[16:17] op_sel_hi:[1,0]
	v_exp_f32_e32 v12, v12
	v_exp_f32_e32 v13, v13
	v_exp_f32_e32 v14, v14
	v_exp_f32_e32 v15, v15
	v_exp_f32_e32 v8, v8
	v_exp_f32_e32 v9, v9
	v_exp_f32_e32 v10, v10
	v_exp_f32_e32 v11, v11
	v_pk_mul_f32 v[6:7], v[6:7], v[16:17] op_sel_hi:[1,0]
	v_pk_mul_f32 v[4:5], v[4:5], v[16:17] op_sel_hi:[1,0]
	v_pk_add_f32 v[14:15], v[14:15], 1.0 op_sel_hi:[1,0]
	v_pk_add_f32 v[12:13], v[12:13], 1.0 op_sel_hi:[1,0]
	v_pk_add_f32 v[8:9], v[8:9], 1.0 op_sel_hi:[1,0]
	v_pk_mul_f32 v[2:3], v[2:3], v[16:17] op_sel_hi:[1,0]
	v_pk_mul_f32 v[0:1], v[0:1], v[16:17] op_sel_hi:[1,0]
	v_exp_f32_e32 v4, v4
	v_exp_f32_e32 v5, v5
	v_exp_f32_e32 v6, v6
	v_exp_f32_e32 v7, v7
	v_pk_add_f32 v[10:11], v[10:11], 1.0 op_sel_hi:[1,0]
	v_rcp_f32_e32 v12, v12
	v_rcp_f32_e32 v13, v13
	v_rcp_f32_e32 v14, v14
	v_rcp_f32_e32 v15, v15
	v_rcp_f32_e32 v18, v8
	v_rcp_f32_e32 v19, v9
	v_exp_f32_e32 v0, v0
	v_exp_f32_e32 v2, v2
	v_exp_f32_e32 v3, v3
	v_exp_f32_e32 v1, v1
	v_rcp_f32_e32 v20, v10
	v_rcp_f32_e32 v21, v11
	s_waitcnt vmcnt(14)
	v_lshlrev_b32_e32 v8, 16, v76
	v_and_b32_e32 v9, 0xffff0000, v76
	v_lshlrev_b32_e32 v10, 16, v77
	v_and_b32_e32 v11, 0xffff0000, v77
	v_lshlrev_b32_e32 v22, 16, v78
	v_and_b32_e32 v23, 0xffff0000, v78
	v_and_b32_e32 v27, 0xffff0000, v72
	v_lshlrev_b32_e32 v28, 16, v73
	v_and_b32_e32 v29, 0xffff0000, v73
	v_lshlrev_b32_e32 v30, 16, v74
	v_and_b32_e32 v31, 0xffff0000, v74
	v_pk_add_f32 v[6:7], v[6:7], 1.0 op_sel_hi:[1,0]
	v_pk_add_f32 v[4:5], v[4:5], 1.0 op_sel_hi:[1,0]
	v_lshlrev_b32_e32 v24, 16, v79
	v_and_b32_e32 v25, 0xffff0000, v79
	v_lshlrev_b32_e32 v32, 16, v75
	v_and_b32_e32 v33, 0xffff0000, v75
	v_pk_fma_f32 v[10:11], v[14:15], v[28:29], v[10:11]
	v_pk_fma_f32 v[8:9], v[12:13], v[26:27], v[8:9]
	v_pk_fma_f32 v[12:13], v[18:19], v[30:31], v[22:23]
	v_lshl_add_u64 v[18:19], v[112:113], 2, s[50:51]
	v_pk_add_f32 v[2:3], v[2:3], 1.0 op_sel_hi:[1,0]
	v_pk_add_f32 v[0:1], v[0:1], 1.0 op_sel_hi:[1,0]
	v_rcp_f32_e32 v4, v4
	v_rcp_f32_e32 v5, v5
	v_rcp_f32_e32 v6, v6
	v_rcp_f32_e32 v7, v7
	v_pk_fma_f32 v[14:15], v[20:21], v[32:33], v[24:25]
	global_store_dwordx4 v[18:19], v[8:11], off nt
	global_store_dwordx4 v[18:19], v[12:15], off offset:16 nt
	s_waitcnt vmcnt(15)
	v_lshlrev_b32_e32 v16, 16, v64
	v_rcp_f32_e32 v8, v0
	v_rcp_f32_e32 v9, v1
	v_rcp_f32_e32 v10, v2
	v_rcp_f32_e32 v11, v3
	s_waitcnt vmcnt(14)
	v_lshlrev_b32_e32 v0, 16, v68
	v_and_b32_e32 v1, 0xffff0000, v68
	v_lshlrev_b32_e32 v2, 16, v69
	v_and_b32_e32 v3, 0xffff0000, v69
	v_and_b32_e32 v17, 0xffff0000, v64
	v_lshlrev_b32_e32 v20, 16, v65
	v_and_b32_e32 v21, 0xffff0000, v65
	v_lshlrev_b32_e32 v12, 16, v70
	v_and_b32_e32 v13, 0xffff0000, v70
	v_lshlrev_b32_e32 v14, 16, v71
	v_and_b32_e32 v15, 0xffff0000, v71
	v_lshlrev_b32_e32 v22, 16, v66
	v_and_b32_e32 v23, 0xffff0000, v66
	v_lshlrev_b32_e32 v24, 16, v67
	v_and_b32_e32 v25, 0xffff0000, v67
	v_pk_fma_f32 v[2:3], v[6:7], v[20:21], v[2:3]
	v_pk_fma_f32 v[0:1], v[4:5], v[16:17], v[0:1]
	s_andn2_b64 vcc, exec, s[0:1]
	s_mov_b64 s[0:1], -1
	v_pk_fma_f32 v[6:7], v[10:11], v[24:25], v[14:15]
	v_pk_fma_f32 v[4:5], v[8:9], v[22:23], v[12:13]
	global_store_dwordx4 v[18:19], v[0:3], off offset:512 nt
	global_store_dwordx4 v[18:19], v[4:7], off offset:528 nt
	s_cbranch_vccnz .LBB0_1025
	s_andn2_b64 vcc, exec, s[10:11]
	s_cbranch_vccnz .LBB0_1024
	s_barrier
	s_branch .LBB0_1024
